# s_waitcnt merge (duplicate vmcnt(3) removed) + VALU-to-SALU lane-select masks in scan loops, on top of fast-path rescale flag
# baseline (speedup 1.0000x reference)
; #define SWRITEA(b) do { *(bf16x8*)(V_lds + (b) * SHM_V + vst0) = vsA0; *(bf16x8*)(V_lds + (b) * SHM_V + vst1) = vsA1; *(bf16x8*)(K_lds + (b) * SHM_K + kst) = ksA; } while (0)
; #define SWAIT() asm volatile("s_waitcnt vmcnt(3)" ::: "memory")
; #define RESC(a) do { if (__any((a) < 1.f)) { if (hi == 0) al_l[r32] = (a); asm volatile("s_waitcnt lgkmcnt(0)" ::: "memory"); \
;     _Pragma("unroll") for (int d = 0; d < 4; ++d) _Pragma("unroll") for (int r = 0; r < 16; ++r) o[d][r] *= al_l[crow(r, hi)]; } } while (0)
; DI void attn_pass(const bf16_t* __restrict__ Qb, const bf16_t* __restrict__ Kh, const bf16_t* __restrict__ Vh, int seq, char* lds, f32x16 (&o)[4], float& l_out) {
;     ...
;         __syncthreads(); SWAIT(); SWRITEA(0);
;         RESC(alB); __syncthreads();
.LBB0_1040:
	s_barrier
	s_waitcnt vmcnt(3)
	ds_write_b128 v214, v[160:163]
	ds_write_b128 v215, v[164:167]
	ds_write_b128 v213, v[168:171] offset:32768
	s_cbranch_vccz .LBB0_1044
	s_and_saveexec_b64 s[4:5], s[6:7]
	ds_write_b32 v212, v224 offset:49280
	s_or_b64 exec, exec, s[4:5]
	s_waitcnt lgkmcnt(0)
	v_add_u32_e32 v108, v211, v184
	ds_read_b128 v[96:99], v108 offset:49376
	ds_read_b128 v[100:103], v108 offset:49344
	ds_read_b128 v[104:107], v108 offset:49312
	ds_read_b128 v[108:111], v108 offset:49280
	s_waitcnt lgkmcnt(3)
	v_pk_mul_f32 v[60:61], v[60:61], v[96:97]
	s_waitcnt lgkmcnt(2)
	v_pk_mul_f32 v[56:57], v[56:57], v[100:101]
	s_waitcnt lgkmcnt(1)
	v_pk_mul_f32 v[52:53], v[52:53], v[104:105]
	v_pk_mul_f32 v[62:63], v[62:63], v[98:99]
	v_pk_mul_f32 v[58:59], v[58:59], v[102:103]
	v_pk_mul_f32 v[54:55], v[54:55], v[106:107]
	s_waitcnt lgkmcnt(0)
	v_pk_mul_f32 v[50:51], v[50:51], v[110:111]
	v_pk_mul_f32 v[48:49], v[48:49], v[108:109]
	v_pk_mul_f32 v[44:45], v[96:97], v[44:45]
	v_pk_mul_f32 v[40:41], v[100:101], v[40:41]
	v_pk_mul_f32 v[36:37], v[104:105], v[36:37]
	v_pk_mul_f32 v[46:47], v[98:99], v[46:47]
	v_pk_mul_f32 v[42:43], v[102:103], v[42:43]
	v_pk_mul_f32 v[38:39], v[106:107], v[38:39]
	v_pk_mul_f32 v[34:35], v[110:111], v[34:35]
	v_pk_mul_f32 v[32:33], v[108:109], v[32:33]
	v_pk_mul_f32 v[28:29], v[96:97], v[28:29]
	v_pk_mul_f32 v[24:25], v[100:101], v[24:25]
	v_pk_mul_f32 v[20:21], v[104:105], v[20:21]
	v_pk_mul_f32 v[30:31], v[98:99], v[30:31]
	v_pk_mul_f32 v[26:27], v[102:103], v[26:27]
	v_pk_mul_f32 v[22:23], v[106:107], v[22:23]
	v_pk_mul_f32 v[18:19], v[110:111], v[18:19]
	v_pk_mul_f32 v[16:17], v[108:109], v[16:17]
	v_pk_mul_f32 v[12:13], v[96:97], v[12:13]
	v_pk_mul_f32 v[8:9], v[100:101], v[8:9]
	v_pk_mul_f32 v[4:5], v[104:105], v[4:5]
	v_pk_mul_f32 v[14:15], v[98:99], v[14:15]
	v_pk_mul_f32 v[10:11], v[102:103], v[10:11]
	v_pk_mul_f32 v[6:7], v[106:107], v[6:7]
	v_pk_mul_f32 v[2:3], v[110:111], v[2:3]
	v_pk_mul_f32 v[0:1], v[108:109], v[0:1]
